# P1 GEMM: first two vmcnt waits of a tile's first K-iteration skipped when the tile follows an epilogue (its K-tiles 0/1 already landed; avoids waiting on epilogue store acks)
# baseline (speedup 1.0000x reference)
;     __host__ __device__ bool next(int i, Unit& u) const { Unit v; if (!inner.next(i >> 1, v)) return false; u.pm = v.pm; u.pn = 2 * v.pn + (i & 1); return true; }
; #define PG8_WAIT_V(n) asm volatile("s_waitcnt vmcnt(" #n ")" ::: "memory")
;     int tid_ = threadIdx.x; asm volatile("" : "+v"(tid_));
;     const int tid = tid_, wid = __builtin_amdgcn_readfirstlane(tid >> 6), lane = tid & 63, wr = wid >> 2, wc = wid & 3, fr = lane & 15, fq = lane >> 4;
;     const int K = g.K, nt = K / BK;
;     unsigned voffA[2], voffB[2];
; #pragma unroll
;     for (int i = 0; i < 2; ++i) { int R, C; stage_rc(tid * 16 + i * 8192, R, C); const int Rb = Epi::PERM ? ((R & ~31) + perm32(R & 31)) : R;
;         voffA[i] = (unsigned)(R * g.lda + C) * 2u; voffB[i] = (unsigned)(Rb * K + C) * 2u; }
;     const size_t kstep = (size_t)(BK * 2);
;     const size_t hstepA = (size_t)HALF * g.lda * 2, hstepB = (size_t)HALF * K * 2;
;     const size_t tstepA = 2 * hstepA, tstepB = 2 * hstepB;
;     const unsigned ldsw = (unsigned)wid * 1024u;
;     const int aoff = lds_byte(wr * 64 + fr, fq * 8), boff = lds_byte(wc * 32 + fr, fq * 8);
;     ...
;     Unit cur, nxt; int ui = 0;
;     if (!S.next(0, cur)) return;
;     f32x4 acc[2][2][4][2];
; #pragma unroll
;     for (int a = 0; a < 2; ++a)
; #pragma unroll
;         for (int b = 0; b < 2; ++b)
; #pragma unroll
;             for (int m = 0; m < 4; ++m)
; #pragma unroll
;                 for (int n = 0; n < 2; ++n) acc[a][b][m][n] = (f32x4){0.f, 0.f, 0.f, 0.f};
;     bf16x8 At[4][2], B0[2][2], B1[2][2];
;     const char* cA = (const char*)g.A + (size_t)cur.pm * tstepA; const char* cB = (const char*)g.Bt + (size_t)cur.pn * tstepB;
;     S.a_ready(cur);
;     if constexpr (SP2) {
;         PG8_STAGE(PG8_SB(0, 0), cB, voffB); PG8_STAGE(PG8_SB(0, 1), cB + hstepB, voffB); PG8_STAGE(PG8_SA(0, 0), cA, voffA); PG8_STAGE(PG8_SA(0, 1), cA + hstepA, voffA);
;         if (wr == 1) PG8_BAR;
;         PG8_WAIT_V(2); PG8_BAR;
;         PG8_STAGE(PG8_SB(1, 0), cB + kstep, voffB); PG8_STAGE(PG8_SA(1, 0), cA + kstep, voffA); PG8_STAGE(PG8_SB(1, 1), cB + hstepB + kstep, voffB);
;         PG8_WAIT_V(6); PG8_BAR;
;     } else {
;         PG8_STAGE(PG8_SB(0, 0), cB, voffB); PG8_STAGE(PG8_SA(0, 0), cA, voffA); PG8_STAGE(PG8_SB(0, 1), cB + hstepB, voffB); PG8_STAGE(PG8_SA(0, 1), cA + hstepA, voffA);
;         if (wr == 1) PG8_BAR;
;         PG8_WAIT_V(4); PG8_BAR;
.LBB0_319:
	s_mov_b32 s101, 1
	s_bitcmp0_b32 s20, 0
	s_cselect_b64 s[2:3], -1, 0
	v_writelane_b32 v255, s2, 13
	v_readlane_b32 s36, v252, 1
	v_readlane_b32 s49, v252, 14
	v_writelane_b32 v255, s3, 14
	s_and_b64 s[2:3], s[2:3], exec
	v_readlane_b32 s51, v252, 16
	s_mov_b64 s[0:1], 0x1ed00000
	v_readlane_b32 s48, v252, 13
	v_readlane_b32 s50, v252, 15
	s_cselect_b32 s2, s51, s49
	v_writelane_b32 v255, s2, 15
	s_cselect_b32 s2, s50, s48
	v_readlane_b32 s10, v253, 54
	s_mov_b64 s[0:1], 0
	v_writelane_b32 v255, s2, 16
	s_mov_b64 s[2:3], 0x6c00000
	s_mov_b64 s[12:13], 0xec00000
	s_mov_b64 s[4:5], 0x12c00000
	s_mov_b64 s[6:7], 0x16c00000
	s_mov_b64 s[8:9], 0x1ac00000
	v_mov_b32_e32 v5, v232
	v_readlane_b32 s11, v253, 55
	s_andn2_b64 vcc, exec, s[10:11]
	v_readfirstlane_b32 s10, v5
	v_readlane_b32 s37, v252, 2
	v_readlane_b32 s38, v252, 3
	v_readlane_b32 s39, v252, 4
	v_readlane_b32 s40, v252, 5
	v_readlane_b32 s41, v252, 6
	v_readlane_b32 s42, v252, 7
	v_readlane_b32 s43, v252, 8
	v_readlane_b32 s44, v252, 9
	v_readlane_b32 s45, v252, 10
	v_readlane_b32 s46, v252, 11
	v_readlane_b32 s47, v252, 12
	s_cbranch_vccnz .LBB0_399
	v_lshlrev_b32_e32 v0, 4, v5
	v_add_u32_e32 v1, 0x2000, v0
	v_ashrrev_i32_e32 v2, 31, v1
	v_lshrrev_b32_e32 v2, 22, v2
	v_add_u32_e32 v2, v1, v2
	v_ashrrev_i32_e32 v4, 10, v2
	v_mul_i32_i24_e32 v2, 0x400, v4
	v_sub_u32_e32 v1, v1, v2
	v_lshrrev_b32_e32 v2, 4, v1
	v_bitop3_b32 v1, v2, v1, 32 bitop3:0x6c
	v_ashrrev_i32_e32 v2, 31, v1
	v_lshrrev_b32_e32 v2, 26, v2
	v_add_u32_e32 v2, v1, v2
	v_lshlrev_b32_e32 v3, 3, v4
	v_readlane_b32 s11, v255, 16
	v_ashrrev_i32_e32 v6, 6, v2
	v_and_b32_e32 v3, -16, v3
	s_add_u32 s46, s11, s0
	v_readlane_b32 s0, v255, 15
	v_add_u32_e32 v3, v6, v3
	s_addc_u32 s47, s0, s1
	v_and_b32_e32 v7, 3, v6
	s_mov_b32 s0, 0x3fffe0
	v_lshrrev_b32_e32 v8, 2, v3
	v_lshlrev_b32_e32 v9, 1, v3
	v_and_b32_e32 v2, 0xc0, v2
	v_and_or_b32 v7, v3, s0, v7
	v_and_b32_e32 v8, 4, v8
	v_and_b32_e32 v9, 24, v9
	v_sub_u32_e32 v1, v1, v2
	v_or3_b32 v8, v7, v8, v9
	v_lshlrev_b32_e32 v7, 5, v4
	v_ashrrev_i16_sdwa v1, v233, sext(v1) dst_sel:DWORD dst_unused:UNUSED_PAD src0_sel:DWORD src1_sel:BYTE_0
	v_and_b32_e32 v9, 32, v7
	v_bfe_i32 v7, v1, 0, 16
	v_add_lshl_u32 v1, v9, v7, 1
	v_lshl_add_u32 v150, v8, 10, v1
	v_lshl_add_u32 v152, v3, 10, v1
	v_bfe_i32 v1, v5, 27, 1
	v_lshrrev_b32_e32 v1, 22, v1
	v_add_u32_e32 v1, v0, v1
	v_and_b32_e32 v1, 0xfffffc00, v1
	v_sub_u32_e32 v0, v0, v1
	v_lshrrev_b32_e32 v1, 4, v0
	v_ashrrev_i32_e32 v2, 31, v5
	v_bitop3_b32 v0, v1, v0, 32 bitop3:0x6c
	v_lshrrev_b32_e32 v2, 26, v2
	v_ashrrev_i32_e32 v1, 31, v0
	v_add_u32_e32 v2, v5, v2
	v_lshrrev_b32_e32 v1, 26, v1
	v_ashrrev_i32_e32 v9, 6, v2
	v_add_u32_e32 v1, v0, v1
	v_lshlrev_b32_e32 v2, 3, v9
	v_ashrrev_i32_e32 v8, 6, v1
	v_and_b32_e32 v2, -16, v2
	v_add_u32_e32 v2, v8, v2
	v_and_b32_e32 v3, 3, v8
	v_lshrrev_b32_e32 v10, 2, v2
	v_lshlrev_b32_e32 v11, 1, v2
	v_and_b32_e32 v1, 0xc0, v1
	s_ashr_i32 s11, s10, 6
	v_and_or_b32 v3, v2, s0, v3
	v_and_b32_e32 v10, 4, v10
	v_and_b32_e32 v11, 24, v11
	v_sub_u32_e32 v0, v0, v1
	s_ashr_i32 s14, s10, 8
	s_lshl_b32 s48, s11, 10
	v_or3_b32 v3, v3, v10, v11
	v_lshlrev_b32_e32 v10, 5, v9
	v_ashrrev_i16_sdwa v0, v233, sext(v0) dst_sel:DWORD dst_unused:UNUSED_PAD src0_sel:DWORD src1_sel:BYTE_0
	v_readlane_b32 s0, v254, 13
	v_and_b32_e32 v11, 32, v10
	v_bfe_i32 v10, v0, 0, 16
	v_readlane_b32 s1, v254, 14
	s_add_u32 s22, s46, s0
	v_add_lshl_u32 v0, v11, v10, 1
	s_addc_u32 s23, s47, s1
	s_add_i32 s49, s48, 0
	v_lshl_add_u32 v64, v3, 10, v0
	s_add_i32 m0, s49, 0x10000
	v_lshl_add_u32 v154, v2, 10, v0
	global_load_lds_dwordx4 v64, s[22:23]
	s_add_i32 m0, s49, 0x12000
	s_add_u32 s0, s22, 0x20000
	global_load_lds_dwordx4 v150, s[22:23]
	s_addc_u32 s1, s23, 0
	s_add_i32 m0, s49, 0x14000
	s_add_i32 s50, s49, 0x2000
	global_load_lds_dwordx4 v64, s[0:1]
	s_add_i32 m0, s49, 0x16000
	s_add_i32 s51, s49, 0x4000
	global_load_lds_dwordx4 v150, s[0:1]
	v_readlane_b32 s0, v254, 31
	s_mov_b32 m0, s49
	v_readlane_b32 s1, v254, 32
	s_add_i32 s52, s49, 0x6000
	v_mov_b32_e32 v151, v65
	s_cmp_eq_u32 s14, 1
	v_lshl_add_u64 v[0:1], s[22:23], 0, v[64:65]
	v_lshl_add_u64 v[2:3], s[22:23], 0, v[150:151]
	global_load_lds_dwordx4 v154, s[0:1]
	s_mov_b32 m0, s50
	s_mov_b64 s[24:25], 0x80
	global_load_lds_dwordx4 v152, s[0:1]
	v_readlane_b32 s0, v254, 33
	s_mov_b32 m0, s51
	v_readlane_b32 s1, v254, 34
	s_nop 4
	global_load_lds_dwordx4 v154, s[0:1]
	s_mov_b32 m0, s52
	s_nop 0
	global_load_lds_dwordx4 v152, s[0:1]
	s_cselect_b64 s[0:1], -1, 0
	s_cmp_lg_u32 s14, 1
	s_cbranch_scc1 .LBB0_322
	s_barrier

; #define PG8_STAGE(bufoff, gbase, voff) do { _Pragma("unroll") for (int _i = 0; _i < 2; ++_i) \
;         __builtin_amdgcn_global_load_lds((const unsigned*)((const char*)(gbase) + (voff)[_i]), (PG8_LAS unsigned*)(lds + (bufoff) + ldsw + _i * 8192), 16, 0, 0); } while (0)
; #define PG8_LDA(dst, b, h) do { _Pragma("unroll") for (int m = 0; m < 4; ++m) _Pragma("unroll") for (int k = 0; k < 2; ++k) dst[m][k] = *(const PG8_LAS bf16x8*)(lds + PG8_SA(b, h) + aoff + m * 2048 + k * 1024); } while (0)
; #define PG8_LDB(dst, b, h) do { _Pragma("unroll") for (int n = 0; n < 2; ++n) _Pragma("unroll") for (int k = 0; k < 2; ++k) dst[n][k] = *(const PG8_LAS bf16x8*)(lds + PG8_SB(b, h) + boff + n * 2048 + k * 1024); } while (0)
; #define PG8_WAIT_V(n) asm volatile("s_waitcnt vmcnt(" #n ")" ::: "memory")
; #define PG8_WAIT_L(n) asm volatile("s_waitcnt lgkmcnt(" #n ")" ::: "memory")
; #define PG8_BAR __builtin_amdgcn_s_barrier()
; #define PG8_SCHED __builtin_amdgcn_sched_barrier(0)
;     ...
;             const bool last = (t == nt - 2);
;             const char* a1 = cA + (size_t)(t + 1) * kstep;
;             const char* a2 = last ? nA : cA + (size_t)(t + 2) * kstep; const char* b2 = last ? nB : cB + (size_t)(t + 2) * kstep;
;             const char* a3 = a2 + kstep; const char* b3 = b2 + kstep;
;             if (last && has_next) S.a_ready(nxt);
;             if constexpr (SP2) {
;             PG8_LDB(B0, 0, 0); PG8_LDB(B1, 0, 1); PG8_SCHED; PG8_LDA(At, 0, 0); PG8_STAGE(PG8_SA(1, 1), a1 + hstepA, voffA);
;             PG8_WAIT_V(8); PG8_WAIT_L(0); PG8_BAR; PG8_MMA(0, 0, At, B0); PG8_MMA(0, 1, At, B1); PG8_BAR; PG8_SCHED;
;             PG8_LDA(At, 0, 1); PG8_STAGE(PG8_SB(0, 0), b2, voffB); PG8_STAGE(PG8_SB(0, 1), b2 + hstepB, voffB); PG8_STAGE(PG8_SA(0, 0), a2, voffA);
;             PG8_WAIT_V(8); PG8_WAIT_L(0); PG8_BAR; PG8_MMA(1, 0, At, B0); PG8_MMA(1, 1, At, B1); PG8_BAR; PG8_SCHED;
.LBB0_328:
	s_add_u32 s22, s18, 0xfffe0080
	s_addc_u32 s23, s19, -1
	s_add_i32 s40, 0, 0x10000
	s_cmp_eq_u32 s33, 4
	s_cselect_b32 s39, s11, s23
	s_cselect_b32 s38, s21, s22
	s_cselect_b32 s23, s25, s29
	s_cselect_b32 s22, s26, s27
	s_add_i32 s42, 0, 0x14000
	v_add_u32_e32 v70, s40, v215
	v_add_u32_e32 v168, s42, v215
	ds_read_b128 v[44:47], v70
	ds_read_b128 v[56:59], v70 offset:1024
	ds_read_b128 v[66:69], v70 offset:2048
	ds_read_b128 v[70:73], v70 offset:3072
	s_waitcnt lgkmcnt(0)
	ds_read_b128 v[146:149], v168
	ds_read_b128 v[160:163], v168 offset:1024
	ds_read_b128 v[164:167], v168 offset:2048
	ds_read_b128 v[168:171], v168 offset:3072
	v_lshl_add_u64 v[222:223], s[18:19], 0, v[156:157]
	s_add_i32 m0, s49, 0xc000
	ds_read_b128 v[172:175], v216
	ds_read_b128 v[176:179], v216 offset:1024
	ds_read_b128 v[180:183], v216 offset:2048
	ds_read_b128 v[184:187], v216 offset:3072
	ds_read_b128 v[188:191], v216 offset:4096
	ds_read_b128 v[206:209], v216 offset:5120
	ds_read_b128 v[210:213], v216 offset:6144
	ds_read_b128 v[218:221], v216 offset:7168
	global_load_lds_dwordx4 v[222:223], off
	v_lshl_add_u64 v[222:223], s[18:19], 0, v[158:159]
	s_add_i32 m0, s49, 0xe000
	s_nop 0
	global_load_lds_dwordx4 v[222:223], off
	s_or_b32 s98, s33, s101
	s_cmp_eq_u32 s98, 0
	s_cbranch_scc1 .Lp1_skipw1
	s_waitcnt vmcnt(8)
.Lp1_skipw1:
	s_waitcnt lgkmcnt(0)
	s_barrier
	s_setprio 1
	s_waitcnt lgkmcnt(0)
	v_mfma_i32_16x16x64_i8 v[142:145], v[44:47], v[172:175], v[142:145]
	v_mfma_i32_16x16x64_i8 v[138:141], v[66:69], v[172:175], v[138:141]
	v_mfma_i32_16x16x64_i8 v[126:129], v[44:47], v[180:183], v[126:129]
	v_mfma_i32_16x16x64_i8 v[122:125], v[66:69], v[180:183], v[122:125]
	v_mfma_i32_16x16x64_i8 v[110:113], v[44:47], v[188:191], v[110:113]
	v_mfma_i32_16x16x64_i8 v[106:109], v[66:69], v[188:191], v[106:109]
	v_mfma_i32_16x16x64_i8 v[94:97], v[44:47], v[210:213], v[94:97]
	v_mfma_i32_16x16x64_i8 v[90:93], v[66:69], v[210:213], v[90:93]
	v_mfma_i32_16x16x64_i8 v[142:145], v[56:59], v[176:179], v[142:145]
	v_mfma_i32_16x16x64_i8 v[138:141], v[70:73], v[176:179], v[138:141]
	v_mfma_i32_16x16x64_i8 v[126:129], v[56:59], v[184:187], v[126:129]
	v_mfma_i32_16x16x64_i8 v[122:125], v[70:73], v[184:187], v[122:125]
	v_mfma_i32_16x16x64_i8 v[110:113], v[56:59], v[206:209], v[110:113]
	v_mfma_i32_16x16x64_i8 v[106:109], v[70:73], v[206:209], v[106:109]
	v_mfma_i32_16x16x64_i8 v[94:97], v[56:59], v[218:221], v[94:97]
	v_mfma_i32_16x16x64_i8 v[90:93], v[70:73], v[218:221], v[90:93]
	s_setprio 0
	s_setprio 1
	v_mfma_i32_16x16x64_i8 v[134:137], v[146:149], v[172:175], v[134:137]
	v_mfma_i32_16x16x64_i8 v[130:133], v[164:167], v[172:175], v[130:133]
	v_mfma_i32_16x16x64_i8 v[118:121], v[146:149], v[180:183], v[118:121]
	v_mfma_i32_16x16x64_i8 v[114:117], v[164:167], v[180:183], v[114:117]
	v_mfma_i32_16x16x64_i8 v[102:105], v[146:149], v[188:191], v[102:105]
	v_mfma_i32_16x16x64_i8 v[98:101], v[164:167], v[188:191], v[98:101]
	v_mfma_i32_16x16x64_i8 v[86:89], v[146:149], v[210:213], v[86:89]
	v_mfma_i32_16x16x64_i8 v[82:85], v[164:167], v[210:213], v[82:85]
	v_mfma_i32_16x16x64_i8 v[134:137], v[160:163], v[176:179], v[134:137]
	v_mfma_i32_16x16x64_i8 v[130:133], v[168:171], v[176:179], v[130:133]
	v_mfma_i32_16x16x64_i8 v[118:121], v[160:163], v[184:187], v[118:121]
	v_mfma_i32_16x16x64_i8 v[114:117], v[168:171], v[184:187], v[114:117]
	v_mfma_i32_16x16x64_i8 v[102:105], v[160:163], v[206:209], v[102:105]
	v_mfma_i32_16x16x64_i8 v[98:101], v[168:171], v[206:209], v[98:101]
	v_mfma_i32_16x16x64_i8 v[86:89], v[160:163], v[218:221], v[86:89]
	v_mfma_i32_16x16x64_i8 v[82:85], v[168:171], v[218:221], v[82:85]
	s_setprio 0
	s_barrier
	s_add_i32 s40, s40, s48
	v_lshl_add_u64 v[222:223], s[22:23], 0, v[64:65]
	s_mov_b32 m0, s40
	ds_read_b128 v[172:175], v216 offset:16384
	ds_read_b128 v[176:179], v216 offset:17408
	ds_read_b128 v[180:183], v216 offset:18432
	ds_read_b128 v[184:187], v216 offset:19456
	ds_read_b128 v[188:191], v216 offset:20480
	ds_read_b128 v[206:209], v216 offset:21504
	ds_read_b128 v[210:213], v216 offset:22528
	ds_read_b128 v[218:221], v216 offset:23552
	global_load_lds_dwordx4 v[222:223], off
	s_add_i32 m0, s40, 0x2000
	s_add_u32 s40, s22, 0x20000
	v_lshl_add_u64 v[224:225], s[22:23], 0, v[150:151]
	s_addc_u32 s41, s23, 0
	s_add_i32 s42, s42, s48
	global_load_lds_dwordx4 v[224:225], off
	v_lshl_add_u64 v[226:227], s[40:41], 0, v[64:65]
	s_mov_b32 m0, s42
	v_lshl_add_u64 v[228:229], s[38:39], 0, v[152:153]
	global_load_lds_dwordx4 v[226:227], off
	v_lshl_add_u64 v[226:227], s[40:41], 0, v[150:151]
	s_add_i32 m0, s42, 0x2000
	s_nop 0
	global_load_lds_dwordx4 v[226:227], off
	v_lshl_add_u64 v[226:227], s[38:39], 0, v[154:155]
	s_mov_b32 m0, s49
	s_nop 0
	global_load_lds_dwordx4 v[226:227], off
	s_mov_b32 m0, s50
	s_nop 0
	global_load_lds_dwordx4 v[228:229], off
	s_or_b32 s98, s33, s101
	s_cmp_eq_u32 s98, 0
	s_cbranch_scc1 .Lp1_skipw2
	s_waitcnt vmcnt(8)
; #define PG8_STAGE(bufoff, gbase, voff) do { _Pragma("unroll") for (int _i = 0; _i < 2; ++_i) \
;         __builtin_amdgcn_global_load_lds((const unsigned*)((const char*)(gbase) + (voff)[_i]), (PG8_LAS unsigned*)(lds + (bufoff) + ldsw + _i * 8192), 16, 0, 0); } while (0)
; #define PG8_LDA(dst, b, h) do { _Pragma("unroll") for (int m = 0; m < 4; ++m) _Pragma("unroll") for (int k = 0; k < 2; ++k) dst[m][k] = *(const PG8_LAS bf16x8*)(lds + PG8_SA(b, h) + aoff + m * 2048 + k * 1024); } while (0)
; #define PG8_LDB(dst, b, h) do { _Pragma("unroll") for (int n = 0; n < 2; ++n) _Pragma("unroll") for (int k = 0; k < 2; ++k) dst[n][k] = *(const PG8_LAS bf16x8*)(lds + PG8_SB(b, h) + boff + n * 2048 + k * 1024); } while (0)
; #define PG8_WAIT_V(n) asm volatile("s_waitcnt vmcnt(" #n ")" ::: "memory")
; #define PG8_WAIT_L(n) asm volatile("s_waitcnt lgkmcnt(" #n ")" ::: "memory")
; #define PG8_BAR __builtin_amdgcn_s_barrier()
; #define PG8_SCHED __builtin_amdgcn_sched_barrier(0)
;     ...
;             PG8_WAIT_V(8); PG8_WAIT_L(0); PG8_BAR; PG8_MMA(1, 0, At, B0); PG8_MMA(1, 1, At, B1); PG8_BAR; PG8_SCHED;
;             PG8_LDB(B0, 1, 0); PG8_LDB(B1, 1, 1); PG8_SCHED; PG8_LDA(At, 1, 0); PG8_STAGE(PG8_SA(0, 1), a2 + hstepA, voffA);
;             PG8_WAIT_V(8); PG8_WAIT_L(0); PG8_BAR; PG8_MMA(0, 0, At, B0); PG8_MMA(0, 1, At, B1); PG8_BAR; PG8_SCHED;
.Lp1_skipw2:
	s_waitcnt lgkmcnt(0)
	s_barrier
	s_setprio 1
	s_waitcnt lgkmcnt(0)
	v_mfma_i32_16x16x64_i8 v[78:81], v[44:47], v[172:175], v[78:81]
	v_mfma_i32_16x16x64_i8 v[74:77], v[66:69], v[172:175], v[74:77]
	v_mfma_i32_16x16x64_i8 v[48:51], v[44:47], v[180:183], v[48:51]
	v_mfma_i32_16x16x64_i8 v[40:43], v[66:69], v[180:183], v[40:43]
	v_mfma_i32_16x16x64_i8 v[28:31], v[44:47], v[188:191], v[28:31]
	v_mfma_i32_16x16x64_i8 v[24:27], v[66:69], v[188:191], v[24:27]
	v_mfma_i32_16x16x64_i8 v[12:15], v[44:47], v[210:213], v[12:15]
	v_mfma_i32_16x16x64_i8 v[8:11], v[66:69], v[210:213], v[8:11]
	v_mfma_i32_16x16x64_i8 v[78:81], v[56:59], v[176:179], v[78:81]
	v_mfma_i32_16x16x64_i8 v[74:77], v[70:73], v[176:179], v[74:77]
	v_mfma_i32_16x16x64_i8 v[48:51], v[56:59], v[184:187], v[48:51]
	v_mfma_i32_16x16x64_i8 v[40:43], v[70:73], v[184:187], v[40:43]
	v_mfma_i32_16x16x64_i8 v[28:31], v[56:59], v[206:209], v[28:31]
	v_mfma_i32_16x16x64_i8 v[24:27], v[70:73], v[206:209], v[24:27]
	v_mfma_i32_16x16x64_i8 v[12:15], v[56:59], v[218:221], v[12:15]
	v_mfma_i32_16x16x64_i8 v[8:11], v[70:73], v[218:221], v[8:11]
	s_setprio 0
	s_setprio 1
	v_mfma_i32_16x16x64_i8 v[52:55], v[164:167], v[172:175], v[52:55]
	v_mfma_i32_16x16x64_i8 v[36:39], v[146:149], v[180:183], v[36:39]
	v_mfma_i32_16x16x64_i8 v[32:35], v[164:167], v[180:183], v[32:35]
	v_mfma_i32_16x16x64_i8 v[20:23], v[146:149], v[188:191], v[20:23]
	v_mfma_i32_16x16x64_i8 v[16:19], v[164:167], v[188:191], v[16:19]
	v_mfma_i32_16x16x64_i8 v[4:7], v[146:149], v[210:213], v[4:7]
	v_mfma_i32_16x16x64_i8 v[0:3], v[164:167], v[210:213], v[0:3]
	v_mfma_i32_16x16x64_i8 v[44:47], v[146:149], v[172:175], v[60:63]
	v_mfma_i32_16x16x64_i8 v[52:55], v[168:171], v[176:179], v[52:55]
	v_mfma_i32_16x16x64_i8 v[36:39], v[160:163], v[184:187], v[36:39]
	v_mfma_i32_16x16x64_i8 v[32:35], v[168:171], v[184:187], v[32:35]
	v_mfma_i32_16x16x64_i8 v[20:23], v[160:163], v[206:209], v[20:23]
	v_mfma_i32_16x16x64_i8 v[16:19], v[168:171], v[206:209], v[16:19]
	v_mfma_i32_16x16x64_i8 v[4:7], v[160:163], v[218:221], v[4:7]
	v_mfma_i32_16x16x64_i8 v[0:3], v[168:171], v[218:221], v[0:3]
	v_mfma_i32_16x16x64_i8 v[44:47], v[160:163], v[176:179], v[44:47]
	s_setprio 0
	s_barrier
	s_add_i32 s40, 0, 0x18000
	s_add_i32 s41, 0, 0x1c000
	v_add_u32_e32 v70, s40, v215
	v_add_u32_e32 v168, s41, v215
	ds_read_b128 v[56:59], v70
	ds_read_b128 v[60:63], v70 offset:1024
	ds_read_b128 v[66:69], v70 offset:2048
	ds_read_b128 v[70:73], v70 offset:3072
	ds_read_b128 v[146:149], v168
	ds_read_b128 v[160:163], v168 offset:1024
	ds_read_b128 v[164:167], v168 offset:2048
	ds_read_b128 v[168:171], v168 offset:3072
	s_add_u32 s38, s38, 0x20000
	s_addc_u32 s39, s39, 0
	s_mov_b32 m0, s51
	v_lshl_add_u64 v[230:231], s[38:39], 0, v[154:155]
	ds_read_b128 v[172:175], v216 offset:32768
	ds_read_b128 v[176:179], v216 offset:33792
	ds_read_b128 v[180:183], v216 offset:34816
	ds_read_b128 v[184:187], v216 offset:35840
	ds_read_b128 v[188:191], v216 offset:36864
	ds_read_b128 v[206:209], v216 offset:37888
	ds_read_b128 v[210:213], v216 offset:38912
	ds_read_b128 v[218:221], v216 offset:39936
	global_load_lds_dwordx4 v[230:231], off
	v_lshl_add_u64 v[230:231], s[38:39], 0, v[152:153]
	s_mov_b32 m0, s52
	s_nop 0
	global_load_lds_dwordx4 v[230:231], off
	s_waitcnt vmcnt(8)
	s_waitcnt lgkmcnt(0)
	s_barrier
	s_setprio 1
	s_waitcnt lgkmcnt(0)
	v_mfma_i32_16x16x64_i8 v[142:145], v[56:59], v[172:175], v[142:145]
	v_mfma_i32_16x16x64_i8 v[138:141], v[66:69], v[172:175], v[138:141]
	v_mfma_i32_16x16x64_i8 v[126:129], v[56:59], v[180:183], v[126:129]
	v_mfma_i32_16x16x64_i8 v[122:125], v[66:69], v[180:183], v[122:125]
	v_mfma_i32_16x16x64_i8 v[110:113], v[56:59], v[188:191], v[110:113]
	v_mfma_i32_16x16x64_i8 v[106:109], v[66:69], v[188:191], v[106:109]
	v_mfma_i32_16x16x64_i8 v[94:97], v[56:59], v[210:213], v[94:97]
	v_mfma_i32_16x16x64_i8 v[90:93], v[66:69], v[210:213], v[90:93]
	v_mfma_i32_16x16x64_i8 v[142:145], v[60:63], v[176:179], v[142:145]
	v_mfma_i32_16x16x64_i8 v[138:141], v[70:73], v[176:179], v[138:141]
	v_mfma_i32_16x16x64_i8 v[126:129], v[60:63], v[184:187], v[126:129]
	v_mfma_i32_16x16x64_i8 v[122:125], v[70:73], v[184:187], v[122:125]
	v_mfma_i32_16x16x64_i8 v[110:113], v[60:63], v[206:209], v[110:113]
	v_mfma_i32_16x16x64_i8 v[106:109], v[70:73], v[206:209], v[106:109]
	v_mfma_i32_16x16x64_i8 v[94:97], v[60:63], v[218:221], v[94:97]
	v_mfma_i32_16x16x64_i8 v[90:93], v[70:73], v[218:221], v[90:93]
	s_setprio 0
	s_setprio 1
	v_mfma_i32_16x16x64_i8 v[134:137], v[146:149], v[172:175], v[134:137]
	v_mfma_i32_16x16x64_i8 v[130:133], v[164:167], v[172:175], v[130:133]
	v_mfma_i32_16x16x64_i8 v[118:121], v[146:149], v[180:183], v[118:121]
	v_mfma_i32_16x16x64_i8 v[114:117], v[164:167], v[180:183], v[114:117]
	v_mfma_i32_16x16x64_i8 v[102:105], v[146:149], v[188:191], v[102:105]
	v_mfma_i32_16x16x64_i8 v[98:101], v[164:167], v[188:191], v[98:101]
	v_mfma_i32_16x16x64_i8 v[86:89], v[146:149], v[210:213], v[86:89]
	v_mfma_i32_16x16x64_i8 v[82:85], v[164:167], v[210:213], v[82:85]
	v_mfma_i32_16x16x64_i8 v[134:137], v[160:163], v[176:179], v[134:137]
	v_mfma_i32_16x16x64_i8 v[130:133], v[168:171], v[176:179], v[130:133]
	v_mfma_i32_16x16x64_i8 v[118:121], v[160:163], v[184:187], v[118:121]
	v_mfma_i32_16x16x64_i8 v[114:117], v[168:171], v[184:187], v[114:117]
	v_mfma_i32_16x16x64_i8 v[102:105], v[160:163], v[206:209], v[102:105]
	v_mfma_i32_16x16x64_i8 v[98:101], v[168:171], v[206:209], v[98:101]
	v_mfma_i32_16x16x64_i8 v[86:89], v[160:163], v[218:221], v[86:89]
	v_mfma_i32_16x16x64_i8 v[82:85], v[168:171], v[218:221], v[82:85]
	s_setprio 0
	s_barrier
; #define PG8_STAGE(bufoff, gbase, voff) do { _Pragma("unroll") for (int _i = 0; _i < 2; ++_i) \
;         __builtin_amdgcn_global_load_lds((const unsigned*)((const char*)(gbase) + (voff)[_i]), (PG8_LAS unsigned*)(lds + (bufoff) + ldsw + _i * 8192), 16, 0, 0); } while (0)
; #define PG8_LDA(dst, b, h) do { _Pragma("unroll") for (int m = 0; m < 4; ++m) _Pragma("unroll") for (int k = 0; k < 2; ++k) dst[m][k] = *(const PG8_LAS bf16x8*)(lds + PG8_SA(b, h) + aoff + m * 2048 + k * 1024); } while (0)
; #define PG8_WAIT_V(n) asm volatile("s_waitcnt vmcnt(" #n ")" ::: "memory")
; #define PG8_WAIT_L(n) asm volatile("s_waitcnt lgkmcnt(" #n ")" ::: "memory")
; #define PG8_BAR __builtin_amdgcn_s_barrier()
; #define PG8_SCHED __builtin_amdgcn_sched_barrier(0)
;     __device__ __forceinline__ void operator()(const f32x4 (&acc)[2][2][4][2], const Unit& u, int wr, int wc, int fr, int fq) const {
;     ...
;         const int row0 = u.pm * BM + wr * 64 + fr, cw = wc * 32 + 8 * fq;
;         const int pn = Q ? p1_qtile(u.pn) : u.pn + P1_F0;
;         float rsc[2][4]; f32x4 cs[2][2];
; #pragma unroll
;         for (int ai = 0; ai < 2; ++ai)
; #pragma unroll
;             for (int m = 0; m < 4; ++m) rsc[ai][m] = Q ? XS[row0 + ai * HALF + m * 16] * (1.f / (127.f * 127.f)) : 1.f;
; #pragma unroll
;         for (int bj = 0; bj < 2; ++bj)
; #pragma unroll
;             for (int n = 0; n < 2; ++n) cs[bj][n] = Q ? *(const f32x4*)(CS + u.pn * BM + bj * HALF + cw + 4 * n) : (f32x4){1.f, 1.f, 1.f, 1.f};
;     ...
;             PG8_WAIT_V(8); PG8_WAIT_L(0); PG8_BAR; PG8_MMA(0, 0, At, B0); PG8_MMA(0, 1, At, B1); PG8_BAR; PG8_SCHED;
;             PG8_LDA(At, 1, 1); PG8_STAGE(PG8_SB(1, 0), b3, voffB); PG8_STAGE(PG8_SB(1, 1), b3 + hstepB, voffB); PG8_STAGE(PG8_SA(1, 0), a3, voffA);
;             PG8_WAIT_V(8); PG8_WAIT_L(0); PG8_BAR; PG8_MMA(1, 0, At, B0); PG8_MMA(1, 1, At, B1); PG8_BAR; PG8_SCHED;
	s_add_i32 s38, s40, s48
	v_lshl_add_u64 v[222:223], v[222:223], 0, s[44:45]
	s_mov_b32 m0, s38
	ds_read_b128 v[172:175], v216 offset:49152
	ds_read_b128 v[176:179], v216 offset:50176
	ds_read_b128 v[180:183], v216 offset:51200
	ds_read_b128 v[184:187], v216 offset:52224
	ds_read_b128 v[188:191], v216 offset:53248
	ds_read_b128 v[206:209], v216 offset:54272
	ds_read_b128 v[210:213], v216 offset:55296
	ds_read_b128 v[218:221], v216 offset:56320
	global_load_lds_dwordx4 v[222:223], off
	s_add_i32 m0, s38, 0x2000
	s_add_u32 s22, s22, 0x20080
	v_lshl_add_u64 v[222:223], v[224:225], 0, s[44:45]
	s_addc_u32 s23, s23, 0
	s_add_i32 s38, s41, s48
	global_load_lds_dwordx4 v[222:223], off
	v_lshl_add_u64 v[222:223], s[22:23], 0, v[64:65]
	s_mov_b32 m0, s38
	s_nop 0
	global_load_lds_dwordx4 v[222:223], off
	v_lshl_add_u64 v[222:223], s[22:23], 0, v[150:151]
	s_add_i32 m0, s38, 0x2000
	s_nop 0
	global_load_lds_dwordx4 v[222:223], off
	v_lshl_add_u64 v[222:223], v[226:227], 0, s[44:45]
	s_mov_b32 m0, s58
	s_nop 0
	global_load_lds_dwordx4 v[222:223], off
	v_lshl_add_u64 v[222:223], v[228:229], 0, s[44:45]
	s_mov_b32 m0, s59
	s_nop 0
	global_load_lds_dwordx4 v[222:223], off
	s_waitcnt vmcnt(8)
	s_waitcnt lgkmcnt(0)
	s_barrier
	s_setprio 1
	s_waitcnt lgkmcnt(0)
	v_mfma_i32_16x16x64_i8 v[78:81], v[56:59], v[172:175], v[78:81]
	v_mfma_i32_16x16x64_i8 v[74:77], v[66:69], v[172:175], v[74:77]
	v_mfma_i32_16x16x64_i8 v[48:51], v[56:59], v[180:183], v[48:51]
	v_mfma_i32_16x16x64_i8 v[40:43], v[66:69], v[180:183], v[40:43]
	v_mfma_i32_16x16x64_i8 v[28:31], v[56:59], v[188:191], v[28:31]
	v_mfma_i32_16x16x64_i8 v[24:27], v[66:69], v[188:191], v[24:27]
	v_mfma_i32_16x16x64_i8 v[12:15], v[56:59], v[210:213], v[12:15]
	v_mfma_i32_16x16x64_i8 v[8:11], v[66:69], v[210:213], v[8:11]
	v_mfma_i32_16x16x64_i8 v[78:81], v[60:63], v[176:179], v[78:81]
	v_mfma_i32_16x16x64_i8 v[74:77], v[70:73], v[176:179], v[74:77]
	v_mfma_i32_16x16x64_i8 v[48:51], v[60:63], v[184:187], v[48:51]
	v_mfma_i32_16x16x64_i8 v[40:43], v[70:73], v[184:187], v[40:43]
	v_mfma_i32_16x16x64_i8 v[28:31], v[60:63], v[206:209], v[28:31]
	v_mfma_i32_16x16x64_i8 v[24:27], v[70:73], v[206:209], v[24:27]
	v_mfma_i32_16x16x64_i8 v[12:15], v[60:63], v[218:221], v[12:15]
	v_mfma_i32_16x16x64_i8 v[8:11], v[70:73], v[218:221], v[8:11]
	s_setprio 0
	s_setprio 1
	v_mfma_i32_16x16x64_i8 v[44:47], v[146:149], v[172:175], v[44:47]
	v_mfma_i32_16x16x64_i8 v[60:63], v[160:163], v[176:179], v[44:47]
	v_mfma_i32_16x16x64_i8 v[44:47], v[164:167], v[172:175], v[52:55]
	v_mfma_i32_16x16x64_i8 v[36:39], v[146:149], v[180:183], v[36:39]
	v_mfma_i32_16x16x64_i8 v[32:35], v[164:167], v[180:183], v[32:35]
	v_mfma_i32_16x16x64_i8 v[20:23], v[146:149], v[188:191], v[20:23]
	v_mfma_i32_16x16x64_i8 v[16:19], v[164:167], v[188:191], v[16:19]
	v_mfma_i32_16x16x64_i8 v[4:7], v[146:149], v[210:213], v[4:7]
	v_mfma_i32_16x16x64_i8 v[0:3], v[164:167], v[210:213], v[0:3]
	v_mfma_i32_16x16x64_i8 v[52:55], v[168:171], v[176:179], v[44:47]
	v_mfma_i32_16x16x64_i8 v[36:39], v[160:163], v[184:187], v[36:39]
	v_mfma_i32_16x16x64_i8 v[32:35], v[168:171], v[184:187], v[32:35]
	v_mfma_i32_16x16x64_i8 v[20:23], v[160:163], v[206:209], v[20:23]
	v_mfma_i32_16x16x64_i8 v[16:19], v[168:171], v[206:209], v[16:19]
	v_mfma_i32_16x16x64_i8 v[4:7], v[160:163], v[218:221], v[4:7]
	v_mfma_i32_16x16x64_i8 v[0:3], v[168:171], v[218:221], v[0:3]
	s_setprio 0
	s_barrier
	s_add_i32 s33, s33, 2
	s_add_u32 s18, s18, 0x100
	s_addc_u32 s19, s19, 0
	s_add_u32 s27, s27, 0x100
	s_addc_u32 s29, s29, 0
	s_cmp_gt_u32 s33, 5
	s_cbranch_scc0 .LBB0_328
	s_and_b64 vcc, exec, s[12:13]
	s_cbranch_vccz .LBB0_331
	s_barrier
.LBB0_331:
	s_lshl_b32 s10, s10, 8
	v_mov_b32_e32 v44, v196
	v_mov_b32_e32 v163, v214
	s_add_i32 s10, s10, s56
	s_lshl_b32 s38, s61, 8
	v_add_u32_e32 v188, s10, v44
	v_readlane_b32 s10, v252, 38
	v_ashrrev_i32_e32 v189, 31, v188
	v_readlane_b32 s11, v252, 39
	s_ashr_i32 s39, s38, 31
	v_lshl_add_u32 v206, v163, 3, s57
	v_lshl_add_u64 v[44:45], v[188:189], 2, s[10:11]
	s_lshl_b64 s[10:11], s[38:39], 2
	s_add_u32 s10, s20, s10
	s_addc_u32 s11, s55, s11
	v_ashrrev_i32_e32 v207, 31, v206
	v_lshl_add_u64 v[56:57], v[206:207], 2, s[10:11]
	global_load_dword v146, v[44:45], off
	global_load_dword v147, v[44:45], off offset:64
	global_load_dword v148, v[44:45], off offset:128
	global_load_dword v149, v[44:45], off offset:192
	global_load_dword v162, v[44:45], off offset:512
	global_load_dword v166, v[44:45], off offset:576
	global_load_dword v167, v[44:45], off offset:640
	global_load_dword v171, v[44:45], off offset:704
	global_load_dwordx4 v[66:69], v[56:57], off offset:16
	global_load_dwordx4 v[70:73], v[56:57], off
	s_nop 0
	global_load_dwordx4 v[44:47], v[56:57], off offset:528
	s_nop 0
	global_load_dwordx4 v[56:59], v[56:57], off offset:512
	v_add_u32_e32 v184, 16, v188
	v_add_u32_e32 v180, 32, v188
	v_add_u32_e32 v176, 48, v188
	v_add_u32_e32 v172, 0x80, v188
	v_add_u32_e32 v168, 0x90, v188
	v_add_u32_e32 v164, 0xa0, v188
	v_add_u32_e32 v160, 0xb0, v188
	v_ashrrev_i32_e32 v185, 31, v184
	v_ashrrev_i32_e32 v181, 31, v180
	v_ashrrev_i32_e32 v177, 31, v176
	v_ashrrev_i32_e32 v173, 31, v172
	v_ashrrev_i32_e32 v169, 31, v168
	v_ashrrev_i32_e32 v165, 31, v164
	v_ashrrev_i32_e32 v161, 31, v160
	s_cmp_gt_i32 s61, 7
	s_mov_b64 s[18:19], -1
	s_waitcnt vmcnt(0)
	s_mov_b32 s101, 0
	v_mul_f32_e32 v190, 0x38820610, v146
	v_mul_f32_e32 v186, 0x38820610, v147
	v_mul_f32_e32 v182, 0x38820610, v148
	v_mul_f32_e32 v178, 0x38820610, v149
	v_mul_f32_e32 v174, 0x38820610, v162
	v_mul_f32_e32 v170, 0x38820610, v166
	v_mul_f32_e32 v166, 0x38820610, v167
	v_mul_f32_e32 v162, 0x38820610, v171
	s_cbranch_scc0 .LBB0_342
	s_add_i32 s10, s61, -8
	s_cmp_lt_u32 s10, 4
	s_cselect_b64 s[40:41], -1, 0
	s_and_b64 vcc, exec, s[40:41]
	s_cbranch_vccnz .LBB0_344
	s_lshr_b32 s10, s10, 2
	s_cmp_lt_i32 s10, 2
	s_cbranch_scc1 .LBB0_340
	s_cmp_lt_i32 s10, 3
	s_mov_b64 s[42:43], s[4:5]
	s_cbranch_scc1 .LBB0_339
	s_cmp_lg_u32 s10, 3
	s_cbranch_scc0 .LBB0_337
	s_mov_b64 s[18:19], 0
